# v47 + EpiUp: the remaining 8 scalar silu chunks packed (v_pk_mul/v_pk_add into free temp pairs, rcp results land in the original registers)
# baseline (speedup 1.0000x reference)
;     __device__ __forceinline__ void operator()(Acc& acc, const Unit& u, int wr, int wc, int fr, int fq, LAS unsigned char* lds, int tid) const {
;     ...
;         if constexpr (I8) {
; #pragma unroll
;             for (int ai = 0; ai < 2; ++ai) { const f32x4 sa = ldf4(sx, tok0 + tl0 + 4u * ai);
; #pragma unroll
;                 for (int m = 0; m < 4; ++m)
; #pragma unroll
;                     for (int bj = 0; bj < 2; ++bj)
; #pragma unroll
;                         for (int n = 0; n < 2; ++n) { const pg8::i32x4 iv = __builtin_bit_cast(pg8::i32x4, acc[ai][bj][m][n]); acc[ai][bj][m][n] = __builtin_convertvector(iv, f32x4) * sa[m]; }
;                 asm volatile("" ::: "memory"); }
;         }
;         const unsigned bk = 2 * u.pm + wr;
;         const bool lvalid = (bk & 15) != 0, rvalid = (bk & 15) != 15;
; #pragma unroll
;         for (int bj = 0; bj < 2; ++bj) {
;             const unsigned colp = u.pn * 256 + bj * 128 + wc * 32 + 8 * fq;
;             const unsigned coll = bj * FF + u.pn * 128 + wc * 32 + 8 * fq;
; #pragma unroll
;             for (int n = 0; n < 2; ++n) {
;                 f32x4 c0 = ldf4(cw, coll + 4u * n), c1 = ldf4(cw, (unsigned)FF2 + coll + 4u * n), c2 = ldf4(cw, 2u * FF2 + coll + 4u * n);
;                 if constexpr (I8) { const f32x4 swv = ldf4(sw, colp + 4u * n); c0 = c0 * swv; c1 = c1 * swv; c2 = c2 * swv; }
;                 f32x4 hl = {0.f, 0.f, 0.f, 0.f}, hr = {0.f, 0.f, 0.f, 0.f};
;                 if (fr == 0 && lvalid) hl = ldf4(HALO, (2u * bk) * (unsigned)FF2 + colp + 4u * n);
;                 if (fr == 15 && rvalid) hr = ldf4(HALO, (2u * bk + 1u) * (unsigned)FF2 + colp + 4u * n);
; #pragma unroll
;                 for (int e = 0; e < 4; ++e) {
;                     const float prev = dpp_shr1(hl[e], acc[1][bj][3][n][e]);
;                     const float next = dpp_shl1(hr[e], acc[0][bj][0][n][e]);
;                     float left = prev;
; #pragma unroll
;                     for (int j = 0; j < 8; ++j) {
;                         const float cur = acc[j >> 2][bj][j & 3][n][e];
;                         const float nx = (j < 7) ? acc[(j + 1) >> 2][bj][(j + 1) & 3][n][e] : next;
;                         acc[j >> 2][bj][j & 3][n][e] = c0[e] * left + c1[e] * cur + c2[e] * nx;
;                         left = cur;
;                     }
;                 }
.LBB0_1084:
	s_or_b64 exec, exec, s[44:45]
	v_pk_mul_f32 v[136:137], v[136:137], v[132:133]
	v_pk_mul_f32 v[140:141], v[140:141], v[132:133]
	v_pk_mul_f32 v[120:121], v[136:137], v[120:121]
	v_pk_mul_f32 v[52:53], v[112:113], v[52:53] op_sel:[1,0]
	v_pk_mul_f32 v[138:139], v[138:139], v[134:135]
	v_pk_mul_f32 v[142:143], v[142:143], v[134:135]
	v_pk_mul_f32 v[134:135], v[130:131], v[134:135]
	v_pk_mul_f32 v[130:131], v[128:129], v[132:133]
	v_pk_fma_f32 v[120:121], v[224:225], v[140:141], v[120:121]
	v_pk_fma_f32 v[132:133], v[52:53], v[130:131], v[120:121]
	v_pk_mul_f32 v[120:121], v[52:53], v[140:141]
	v_pk_mul_f32 v[48:49], v[114:115], v[48:49] op_sel_hi:[0,1]
	v_pk_fma_f32 v[120:121], v[224:225], v[136:137], v[120:121]
	v_mov_b32_e32 v208, v115
	v_pk_fma_f32 v[128:129], v[48:49], v[130:131], v[120:121]
	v_pk_mul_f32 v[120:121], v[48:49], v[140:141]
	v_pk_mul_f32 v[44:45], v[208:209], v[44:45] op_sel_hi:[0,1]
	v_pk_fma_f32 v[52:53], v[52:53], v[136:137], v[120:121]
	v_pk_mul_f32 v[40:41], v[104:105], v[40:41] op_sel_hi:[0,1]
	v_pk_fma_f32 v[120:121], v[44:45], v[130:131], v[52:53]
	v_pk_mul_f32 v[52:53], v[44:45], v[140:141]
	v_pk_mul_f32 v[36:37], v[104:105], v[36:37] op_sel:[1,0]
	v_pk_fma_f32 v[48:49], v[48:49], v[136:137], v[52:53]
	v_pk_mul_f32 v[52:53], v[40:41], v[140:141]
	v_pk_mul_f32 v[32:33], v[106:107], v[32:33] op_sel_hi:[0,1]
	v_pk_fma_f32 v[44:45], v[44:45], v[136:137], v[52:53]
	v_pk_mul_f32 v[52:53], v[36:37], v[140:141]
	v_pk_fma_f32 v[48:49], v[40:41], v[130:131], v[48:49]
	v_pk_fma_f32 v[40:41], v[40:41], v[136:137], v[52:53]
	v_pk_mul_f32 v[52:53], v[32:33], v[140:141]
	v_pk_fma_f32 v[44:45], v[36:37], v[130:131], v[44:45]
	v_pk_fma_f32 v[36:37], v[36:37], v[136:137], v[52:53]
	v_pk_mul_f32 v[52:53], v[138:139], v[122:123]
	v_pk_mul_f32 v[54:55], v[112:113], v[54:55] op_sel:[1,0]
	v_pk_fma_f32 v[52:53], v[220:221], v[142:143], v[52:53]
	v_pk_fma_f32 v[40:41], v[32:33], v[130:131], v[40:41]
	v_pk_mul_f32 v[32:33], v[32:33], v[136:137]
	v_pk_fma_f32 v[136:137], v[54:55], v[134:135], v[52:53]
	v_pk_mul_f32 v[52:53], v[54:55], v[142:143]
	v_pk_mul_f32 v[50:51], v[114:115], v[50:51] op_sel_hi:[0,1]
	v_pk_fma_f32 v[32:33], v[222:223], v[140:141], v[32:33]
	v_pk_fma_f32 v[52:53], v[220:221], v[138:139], v[52:53]
	v_pk_fma_f32 v[36:37], v[222:223], v[130:131], v[36:37]
	v_pk_fma_f32 v[32:33], v[130:131], v[124:125], v[32:33]
	v_pk_fma_f32 v[130:131], v[50:51], v[134:135], v[52:53]
	v_pk_mul_f32 v[52:53], v[50:51], v[142:143]
	v_pk_mul_f32 v[46:47], v[208:209], v[46:47] op_sel_hi:[0,1]
	v_pk_fma_f32 v[52:53], v[54:55], v[138:139], v[52:53]
	v_pk_mul_f32 v[42:43], v[104:105], v[42:43] op_sel_hi:[0,1]
	v_pk_fma_f32 v[122:123], v[46:47], v[134:135], v[52:53]
	v_pk_mul_f32 v[52:53], v[46:47], v[142:143]
	v_pk_mul_f32 v[38:39], v[104:105], v[38:39] op_sel:[1,0]
	v_pk_fma_f32 v[50:51], v[50:51], v[138:139], v[52:53]
	v_pk_mul_f32 v[52:53], v[42:43], v[142:143]
	v_pk_mul_f32 v[214:215], v[190:191], v[202:203]
	v_pk_mul_f32 v[190:191], v[188:189], v[200:201]
	v_pk_fma_f32 v[46:47], v[46:47], v[138:139], v[52:53]
	v_pk_mul_f32 v[52:53], v[38:39], v[142:143]
	v_pk_mul_f32 v[124:125], v[112:113], v[26:27] op_sel:[1,0]
	v_pk_mul_f32 v[26:27], v[104:105], v[12:13] op_sel_hi:[0,1]
	v_cvt_f32_i32_e32 v13, v9
	v_cvt_f32_i32_e32 v12, v8
	v_pk_mul_f32 v[196:197], v[196:197], v[200:201]
	v_pk_mul_f32 v[176:177], v[190:191], v[176:177]
	v_pk_mul_f32 v[34:35], v[106:107], v[34:35] op_sel_hi:[0,1]
	v_pk_fma_f32 v[50:51], v[42:43], v[134:135], v[50:51]
	v_pk_fma_f32 v[42:43], v[42:43], v[138:139], v[52:53]
	v_pk_mul_f32 v[100:101], v[112:113], v[100:101] op_sel:[1,0]
	v_pk_mul_f32 v[96:97], v[114:115], v[96:97] op_sel_hi:[0,1]
	v_pk_mul_f32 v[192:193], v[192:193], v[200:201]
	v_pk_fma_f32 v[176:177], v[244:245], v[196:197], v[176:177]
	v_pk_fma_f32 v[42:43], v[34:35], v[134:135], v[42:43]
	v_pk_mul_f32 v[52:53], v[34:35], v[142:143]
	v_pk_mul_f32 v[34:35], v[34:35], v[138:139]
	v_pk_mul_f32 v[92:93], v[208:209], v[92:93] op_sel_hi:[0,1]
	v_pk_fma_f32 v[188:189], v[100:101], v[192:193], v[176:177]
	v_pk_mul_f32 v[176:177], v[100:101], v[196:197]
	v_pk_mul_f32 v[200:201], v[96:97], v[196:197]
	v_pk_fma_f32 v[46:47], v[38:39], v[134:135], v[46:47]
	v_pk_fma_f32 v[38:39], v[38:39], v[138:139], v[52:53]
	v_pk_fma_f32 v[34:35], v[218:219], v[142:143], v[34:35]
	v_mov_b32_e32 v52, v112
	v_mov_b32_e32 v53, v112
	v_pk_mul_f32 v[8:9], v[104:105], v[10:11] op_sel:[1,0]
	v_cvt_f32_i32_e32 v11, v5
	v_cvt_f32_i32_e32 v10, v4
	v_pk_mul_f32 v[88:89], v[104:105], v[88:89] op_sel_hi:[0,1]
	v_pk_fma_f32 v[176:177], v[244:245], v[190:191], v[176:177]
	v_pk_fma_f32 v[100:101], v[100:101], v[190:191], v[200:201]
	v_pk_mul_f32 v[200:201], v[92:93], v[196:197]
	v_pk_fma_f32 v[34:35], v[134:135], v[126:127], v[34:35]
	v_pk_mul_f32 v[126:127], v[52:53], v[30:31]
	v_pk_mul_f32 v[30:31], v[208:209], v[16:17] op_sel_hi:[0,1]
	v_pk_mul_f32 v[16:17], v[104:105], v[12:13] op_sel:[1,0]
	v_cvt_f32_i32_e32 v13, v3
	v_cvt_f32_i32_e32 v12, v2
	v_pk_mul_f32 v[84:85], v[104:105], v[84:85] op_sel:[1,0]
	v_pk_fma_f32 v[176:177], v[96:97], v[192:193], v[176:177]
	v_pk_fma_f32 v[96:97], v[96:97], v[190:191], v[200:201]
	v_pk_mul_f32 v[200:201], v[88:89], v[196:197]
	v_pk_fma_f32 v[100:101], v[92:93], v[192:193], v[100:101]
	v_pk_fma_f32 v[92:93], v[92:93], v[190:191], v[200:201]
	v_pk_mul_f32 v[200:201], v[84:85], v[196:197]
	v_pk_mul_f32 v[78:79], v[106:107], v[78:79] op_sel_hi:[0,1]
	v_pk_mul_f32 v[76:77], v[106:107], v[76:77] op_sel_hi:[0,1]
	v_pk_fma_f32 v[96:97], v[88:89], v[192:193], v[96:97]
	v_pk_fma_f32 v[88:89], v[88:89], v[190:191], v[200:201]
;     __device__ __forceinline__ void operator()(Acc& acc, const Unit& u, int wr, int wc, int fr, int fq, LAS unsigned char* lds, int tid) const {
;     ...
;                         for (int n = 0; n < 2; ++n) { const pg8::i32x4 iv = __builtin_bit_cast(pg8::i32x4, acc[ai][bj][m][n]); acc[ai][bj][m][n] = __builtin_convertvector(iv, f32x4) * sa[m]; }
;                 asm volatile("" ::: "memory"); }
;         }
;         const unsigned bk = 2 * u.pm + wr;
;         const bool lvalid = (bk & 15) != 0, rvalid = (bk & 15) != 15;
; #pragma unroll
;         for (int bj = 0; bj < 2; ++bj) {
;             const unsigned colp = u.pn * 256 + bj * 128 + wc * 32 + 8 * fq;
;             const unsigned coll = bj * FF + u.pn * 128 + wc * 32 + 8 * fq;
; #pragma unroll
;             for (int n = 0; n < 2; ++n) {
;                 f32x4 c0 = ldf4(cw, coll + 4u * n), c1 = ldf4(cw, (unsigned)FF2 + coll + 4u * n), c2 = ldf4(cw, 2u * FF2 + coll + 4u * n);
;                 if constexpr (I8) { const f32x4 swv = ldf4(sw, colp + 4u * n); c0 = c0 * swv; c1 = c1 * swv; c2 = c2 * swv; }
;                 f32x4 hl = {0.f, 0.f, 0.f, 0.f}, hr = {0.f, 0.f, 0.f, 0.f};
;                 if (fr == 0 && lvalid) hl = ldf4(HALO, (2u * bk) * (unsigned)FF2 + colp + 4u * n);
;                 if (fr == 15 && rvalid) hr = ldf4(HALO, (2u * bk + 1u) * (unsigned)FF2 + colp + 4u * n);
; #pragma unroll
;                 for (int e = 0; e < 4; ++e) {
;                     const float prev = dpp_shr1(hl[e], acc[1][bj][3][n][e]);
;                     const float next = dpp_shl1(hr[e], acc[0][bj][0][n][e]);
;                     float left = prev;
; #pragma unroll
;                     for (int j = 0; j < 8; ++j) {
;                         const float cur = acc[j >> 2][bj][j & 3][n][e];
;                         const float nx = (j < 7) ? acc[(j + 1) >> 2][bj][(j + 1) & 3][n][e] : next;
;                         acc[j >> 2][bj][j & 3][n][e] = c0[e] * left + c1[e] * cur + c2[e] * nx;
;                         left = cur;
;                     }
;                 }
;                 asm volatile("" ::: "memory");
;             }
;         }
;         const unsigned colo = u.pn * 128 + wc * 32 + 8 * fq;
; #pragma unroll
;         for (int ai = 0; ai < 2; ++ai)
; #pragma unroll
;             for (int m = 0; m < 4; ++m) {
;                 f32x4 a[2];
; #pragma unroll
;                 for (int n = 0; n < 2; ++n)
	v_pk_mul_f32 v[58:59], v[106:107], v[58:59] op_sel_hi:[0,1]
	v_pk_mul_f32 v[56:57], v[106:107], v[56:57] op_sel_hi:[0,1]
	v_pk_mul_f32 v[4:5], v[106:107], v[6:7] op_sel_hi:[0,1]
	v_pk_mul_f32 v[2:3], v[106:107], v[10:11] op_sel_hi:[0,1]
	v_mov_b32_e32 v106, v107
	v_pk_mul_f32 v[10:11], v[132:133], s[100:101] op_sel_hi:[1,0]
	v_pk_mul_f32 v[198:199], v[198:199], v[202:203]
	v_pk_fma_f32 v[88:89], v[76:77], v[192:193], v[88:89]
	v_pk_mul_f32 v[200:201], v[76:77], v[196:197]
	v_pk_mul_f32 v[76:77], v[76:77], v[190:191]
	v_pk_mul_f32 v[178:179], v[214:215], v[178:179]
	v_cvt_f32_i32_e32 v7, v1
	v_cvt_f32_i32_e32 v6, v0
	v_pk_mul_f32 v[0:1], v[106:107], v[12:13]
	v_exp_f32_e32 v10, v10
	v_exp_f32_e32 v11, v11
	v_pk_mul_f32 v[12:13], v[136:137], s[100:101] op_sel_hi:[1,0]
	v_pk_mul_f32 v[102:103], v[112:113], v[102:103] op_sel:[1,0]
	v_pk_mul_f32 v[98:99], v[114:115], v[98:99] op_sel_hi:[0,1]
	v_pk_mul_f32 v[194:195], v[194:195], v[202:203]
	v_pk_fma_f32 v[92:93], v[84:85], v[192:193], v[92:93]
	v_pk_fma_f32 v[84:85], v[84:85], v[190:191], v[200:201]
	v_pk_fma_f32 v[76:77], v[242:243], v[196:197], v[76:77]
	v_pk_fma_f32 v[178:179], v[240:241], v[198:199], v[178:179]
	v_exp_f32_e32 v12, v12
	v_exp_f32_e32 v13, v13
	v_pk_mul_f32 v[94:95], v[208:209], v[94:95] op_sel_hi:[0,1]
	v_pk_fma_f32 v[84:85], v[242:243], v[192:193], v[84:85]
	v_pk_fma_f32 v[76:77], v[192:193], v[204:205], v[76:77]
	v_pk_fma_f32 v[190:191], v[102:103], v[194:195], v[178:179]
	v_pk_mul_f32 v[178:179], v[102:103], v[198:199]
	v_pk_mul_f32 v[192:193], v[98:99], v[198:199]
	v_pk_mul_f32 v[90:91], v[104:105], v[90:91] op_sel_hi:[0,1]
	v_pk_fma_f32 v[178:179], v[240:241], v[214:215], v[178:179]
	v_pk_fma_f32 v[102:103], v[102:103], v[214:215], v[192:193]
	v_pk_mul_f32 v[192:193], v[94:95], v[198:199]
	v_pk_mul_f32 v[86:87], v[104:105], v[86:87] op_sel:[1,0]
	v_pk_fma_f32 v[178:179], v[98:99], v[194:195], v[178:179]
	v_pk_fma_f32 v[98:99], v[98:99], v[214:215], v[192:193]
	v_pk_mul_f32 v[192:193], v[90:91], v[198:199]
	v_pk_add_f32 v[10:11], v[10:11], 1.0 op_sel_hi:[1,0]
	v_pk_fma_f32 v[102:103], v[94:95], v[194:195], v[102:103]
	v_pk_fma_f32 v[94:95], v[94:95], v[214:215], v[192:193]
	v_pk_mul_f32 v[192:193], v[86:87], v[198:199]
	v_rcp_f32_e32 v10, v10
	v_rcp_f32_e32 v11, v11
	v_pk_add_f32 v[12:13], v[12:13], 1.0 op_sel_hi:[1,0]
	v_pk_fma_f32 v[98:99], v[90:91], v[194:195], v[98:99]
	v_pk_fma_f32 v[90:91], v[90:91], v[214:215], v[192:193]
	v_pk_mul_f32 v[192:193], v[78:79], v[198:199]
	v_pk_mul_f32 v[160:161], v[160:161], v[168:169]
	v_rcp_f32_e32 v12, v12
	v_rcp_f32_e32 v13, v13
	v_pk_fma_f32 v[94:95], v[86:87], v[194:195], v[94:95]
	v_pk_fma_f32 v[86:87], v[86:87], v[214:215], v[192:193]
	v_pk_mul_f32 v[192:193], v[158:159], v[170:171]
	v_pk_mul_f32 v[158:159], v[156:157], v[168:169]
	v_pk_mul_f32 v[144:145], v[160:161], v[144:145]
	v_pk_mul_f32 v[80:81], v[112:113], v[80:81] op_sel:[1,0]
	v_pk_mul_f32 v[72:73], v[114:115], v[72:73] op_sel_hi:[0,1]
	v_pk_mul_f32 v[164:165], v[164:165], v[168:169]
	v_pk_fma_f32 v[144:145], v[236:237], v[158:159], v[144:145]
	v_pk_mul_f32 v[68:69], v[208:209], v[68:69] op_sel_hi:[0,1]
	v_pk_fma_f32 v[156:157], v[80:81], v[164:165], v[144:145]
	v_pk_mul_f32 v[144:145], v[80:81], v[158:159]
	v_pk_mul_f32 v[168:169], v[72:73], v[158:159]
	v_pk_mul_f32 v[10:11], v[132:133], v[10:11]
	v_pk_mul_f32 v[64:65], v[104:105], v[64:65] op_sel_hi:[0,1]
	v_pk_fma_f32 v[144:145], v[236:237], v[160:161], v[144:145]
	v_pk_fma_f32 v[80:81], v[80:81], v[160:161], v[168:169]
	v_pk_mul_f32 v[168:169], v[68:69], v[158:159]
	v_pk_mul_f32 v[106:107], v[10:11], v[188:189]
	v_pk_mul_f32 v[10:11], v[136:137], v[12:13]
	v_pk_mul_f32 v[52:53], v[156:157], s[100:101] op_sel_hi:[1,0]
	v_exp_f32_e32 v52, v52
	v_exp_f32_e32 v53, v53
	v_pk_mul_f32 v[60:61], v[104:105], v[60:61] op_sel:[1,0]
	v_pk_fma_f32 v[144:145], v[72:73], v[164:165], v[144:145]
	v_pk_fma_f32 v[72:73], v[72:73], v[160:161], v[168:169]
	v_pk_mul_f32 v[168:169], v[64:65], v[158:159]
	v_pk_mul_f32 v[162:163], v[162:163], v[170:171]
	v_pk_fma_f32 v[80:81], v[68:69], v[164:165], v[80:81]
	v_pk_fma_f32 v[68:69], v[68:69], v[160:161], v[168:169]
	v_pk_mul_f32 v[168:169], v[60:61], v[158:159]
	v_pk_fma_f32 v[72:73], v[64:65], v[164:165], v[72:73]
	v_pk_fma_f32 v[64:65], v[64:65], v[160:161], v[168:169]
	v_pk_mul_f32 v[146:147], v[162:163], v[146:147]
	v_pk_mul_f32 v[82:83], v[112:113], v[82:83] op_sel:[1,0]
	v_pk_mul_f32 v[166:167], v[166:167], v[170:171]
	v_pk_fma_f32 v[64:65], v[56:57], v[164:165], v[64:65]
	v_pk_mul_f32 v[168:169], v[56:57], v[158:159]
	v_pk_mul_f32 v[56:57], v[56:57], v[160:161]
	v_pk_fma_f32 v[146:147], v[232:233], v[192:193], v[146:147]
	v_pk_fma_f32 v[56:57], v[234:235], v[158:159], v[56:57]
	v_pk_fma_f32 v[158:159], v[82:83], v[166:167], v[146:147]
	v_pk_mul_f32 v[132:133], v[10:11], v[190:191]
	v_pk_add_f32 v[52:53], v[52:53], 1.0 op_sel_hi:[1,0]
	v_pk_mul_f32 v[66:67], v[104:105], v[66:67] op_sel_hi:[0,1]
	v_pk_mul_f32 v[62:63], v[104:105], v[62:63] op_sel:[1,0]
	v_pk_fma_f32 v[38:39], v[218:219], v[134:135], v[38:39]
	v_pk_mul_f32 v[134:135], v[228:229], v[28:29]
	v_pk_mul_f32 v[112:113], v[112:113], v[24:25] op_sel:[1,0]
	v_pk_mul_f32 v[28:29], v[208:209], v[18:19] op_sel_hi:[0,1]
	v_pk_mul_f32 v[24:25], v[104:105], v[14:15] op_sel_hi:[0,1]
	v_rcp_f32_e32 v104, v52
	s_waitcnt vmcnt(0)
;     __device__ bool next(int i, Unit& u) const { return S.next(i, u); }
;     __device__ bool next(int i, Unit& u) const { const int L = i * G + c; if (L >= 3 * 44) return false; u.pm = L % 3; u.pn = L / 3; u.g = 0; u.part = 0; u.keep = 0; return true; }
; __device__ __forceinline__ float silu_f(float x) { return x * __builtin_amdgcn_rcpf(1.0f + __expf(-x)); }
;     __device__ bool next(int i, Unit& u) const {
;         const long L = (long)i * G + c; if (L >= nwg) return false;
;         int wgid = (int)L; { const int q = nwg / NXCD, r = nwg % NXCD, xcd = wgid % NXCD, off = wgid / NXCD; wgid = (xcd < r ? xcd * (q + 1) : r * (q + 1) + (xcd - r) * q) + off; }
;         const int nig = WGM * nN, gid = wgid / nig, fm = gid * WGM, gsz = (nM - fm) < WGM ? (nM - fm) : WGM;
;         u.pm = fm + ((wgid % nig) % gsz); u.pn = (wgid % nig) / gsz; u.g = 0; u.part = 0; u.keep = 0; return true;
;     __device__ __forceinline__ void operator()(Acc& acc, const Unit& u, int wr, int wc, int fr, int fq, LAS unsigned char* lds, int tid) const {
;     ...
;         for (int ai = 0; ai < 2; ++ai)
; #pragma unroll
;             for (int m = 0; m < 4; ++m) {
;                 f32x4 a[2];
; #pragma unroll
;                 for (int n = 0; n < 2; ++n)
; #pragma unroll
;                     for (int e = 0; e < 4; ++e) a[n][e] = silu_f(acc[ai][0][m][n][e]) * acc[ai][1][m][n][e];
;                 store_h8_nt((h16*)((char*)ACT + (((tok0 + tl0 + 4u * ai + m) * (unsigned)FF + colo) << 1)), a[0], a[1]);
	v_pk_mul_f32 v[18:19], v[116:117], v[180:181]
	v_mul_f32_e32 v116, 0xbfb8aa3b, v158
	v_pk_mul_f32 v[6:7], v[226:227], v[6:7]
	v_rcp_f32_e32 v105, v53
	v_pk_mul_f32 v[10:11], v[118:119], v[182:183]
	v_exp_f32_e32 v118, v116
	v_mul_f32_e32 v116, 0xbfb8aa3b, v159
	v_mov_b32_dpp v148, v6 row_shr:1 row_mask:0xf bank_mask:0xf
	v_mov_b32_dpp v149, v7 row_shr:1 row_mask:0xf bank_mask:0xf
	v_exp_f32_e32 v119, v116
	v_pk_mul_f32 v[74:75], v[114:115], v[74:75] op_sel_hi:[0,1]
	v_pk_mul_f32 v[52:53], v[114:115], v[22:23] op_sel_hi:[0,1]
	v_pk_mul_f32 v[54:55], v[114:115], v[20:21] op_sel_hi:[0,1]
	v_pk_mul_f32 v[20:21], v[184:185], v[180:181]
	v_pk_mul_f32 v[114:115], v[18:19], v[148:149]
	v_pk_mul_f32 v[22:23], v[152:153], v[180:181]
	v_pk_fma_f32 v[114:115], v[134:135], v[20:21], v[114:115]
	v_pk_mul_f32 v[104:105], v[156:157], v[104:105]
	v_pk_fma_f32 v[114:115], v[112:113], v[22:23], v[114:115]
	v_mov_b32_dpp v150, v0 row_shr:1 row_mask:0xf bank_mask:0xf
	v_pk_mul_f32 v[116:117], v[104:105], v[114:115]
	v_pk_add_f32 v[104:105], v[118:119], 1.0 op_sel_hi:[1,0]
	v_rcp_f32_e32 v104, v104
	v_rcp_f32_e32 v105, v105
	v_mov_b32_dpp v151, v1 row_shr:1 row_mask:0xf bank_mask:0xf
	v_pk_mul_f32 v[12:13], v[186:187], v[182:183]
	v_pk_mul_f32 v[114:115], v[10:11], v[150:151]
	v_pk_mul_f32 v[14:15], v[154:155], v[182:183]
	v_pk_fma_f32 v[114:115], v[126:127], v[12:13], v[114:115]
	v_pk_mul_f32 v[104:105], v[158:159], v[104:105]
	v_pk_fma_f32 v[114:115], v[124:125], v[14:15], v[114:115]
	s_movk_i32 s0, 0x1600
	v_pk_mul_f32 v[118:119], v[104:105], v[114:115]
	v_pk_mul_f32 v[136:137], v[128:129], s[100:101] op_sel_hi:[1,0]
	v_exp_f32_e32 v136, v136
	v_exp_f32_e32 v137, v137
	v_cvt_pk_f16_f32 v114, v106, v107
	v_mul_lo_u32 v104, v212, s0
	s_mov_b32 s101, s36
	s_mov_b32 s94, s48
	s_mov_b32 s95, s50
	s_mov_b64 s[44:45], s[76:77]
	s_mov_b64 s[60:61], s[56:57]
	s_cmp_eq_u32 s101, 0
	s_cbranch_scc1 .Lh1065_skip
	s_add_i32 s93, s93, 1
	s_mul_i32 s0, s93, s71
	s_mul_hi_u32 s1, s93, s70
	s_add_i32 s1, s1, s0
	s_mul_i32 s0, s93, s70
	s_add_u32 s56, s0, s20
	s_addc_u32 s57, s1, s33
	s_cmp_lt_u32 s56, 0x2100
	s_cselect_b64 s[36:37], exec, 0
	s_cbranch_scc0 .Lh1065_pre
	s_lshr_b32 s1, s56, 3
	s_and_b32 s0, s56, 7
	s_mul_i32 s0, s0, 0x420
	s_add_i32 s0, s0, s1
	s_mul_hi_i32 s1, s0, 0x2e8ba2e9
	s_lshr_b32 s4, s1, 31
	s_ashr_i32 s1, s1, 5
	s_add_i32 s1, s1, s4
	s_lshl_b32 s4, s1, 2
	s_sub_i32 s5, 0xc0, s4
	s_mulk_i32 s1, 0xb0
	s_sub_i32 s0, s0, s1
	s_lshr_b32 s48, s0, 2
	s_and_b32 s0, s0, 3
	s_add_i32 s50, s4, s0

;     __device__ bool next(int i, Unit& u) const { return S.next(i, u); }
;     __device__ bool next(int i, Unit& u) const { const int L = i * G + c; if (L >= 3 * 44) return false; u.pm = L % 3; u.pn = L / 3; u.g = 0; u.part = 0; u.keep = 0; return true; }
; __device__ __forceinline__ float silu_f(float x) { return x * __builtin_amdgcn_rcpf(1.0f + __expf(-x)); }
;     __device__ __forceinline__ void operator()(Acc& acc, const Unit& u, int wr, int wc, int fr, int fq, LAS unsigned char* lds, int tid) const {
;     ...
;                 f32x4 c0 = ldf4(cw, coll + 4u * n), c1 = ldf4(cw, (unsigned)FF2 + coll + 4u * n), c2 = ldf4(cw, 2u * FF2 + coll + 4u * n);
;                 if constexpr (I8) { const f32x4 swv = ldf4(sw, colp + 4u * n); c0 = c0 * swv; c1 = c1 * swv; c2 = c2 * swv; }
;                 f32x4 hl = {0.f, 0.f, 0.f, 0.f}, hr = {0.f, 0.f, 0.f, 0.f};
;                 if (fr == 0 && lvalid) hl = ldf4(HALO, (2u * bk) * (unsigned)FF2 + colp + 4u * n);
;                 if (fr == 15 && rvalid) hr = ldf4(HALO, (2u * bk + 1u) * (unsigned)FF2 + colp + 4u * n);
; #pragma unroll
;                 for (int e = 0; e < 4; ++e) {
;                     const float prev = dpp_shr1(hl[e], acc[1][bj][3][n][e]);
;                     const float next = dpp_shl1(hr[e], acc[0][bj][0][n][e]);
;                     float left = prev;
; #pragma unroll
;                     for (int j = 0; j < 8; ++j) {
;                         const float cur = acc[j >> 2][bj][j & 3][n][e];
;                         const float nx = (j < 7) ? acc[(j + 1) >> 2][bj][(j + 1) & 3][n][e] : next;
;                         acc[j >> 2][bj][j & 3][n][e] = c0[e] * left + c1[e] * cur + c2[e] * nx;
;                         left = cur;
;                     }
;                 }
;                 asm volatile("" ::: "memory");
;             }
;         }
;         const unsigned colo = u.pn * 128 + wc * 32 + 8 * fq;
; #pragma unroll
;         for (int ai = 0; ai < 2; ++ai)
; #pragma unroll
;             for (int m = 0; m < 4; ++m) {
;                 f32x4 a[2];
; #pragma unroll
;                 for (int n = 0; n < 2; ++n)
; #pragma unroll
;                     for (int e = 0; e < 4; ++e) a[n][e] = silu_f(acc[ai][0][m][n][e]) * acc[ai][1][m][n][e];
;                 store_h8_nt((h16*)((char*)ACT + (((tok0 + tl0 + 4u * ai + m) * (unsigned)FF + colo) << 1)), a[0], a[1]);
.Lh1065_skip:
	v_pk_add_f32 v[136:137], v[136:137], 1.0 op_sel_hi:[1,0]
	v_add_lshl_u32 v104, v104, v213, 1
	v_cvt_pk_f16_f32 v115, v132, v133
	v_cvt_pk_f16_f32 v116, v116, v117
	v_cvt_pk_f16_f32 v117, v118, v119
	v_rcp_f32_e32 v106, v136
	v_pk_mul_f32 v[118:119], v[130:131], s[100:101] op_sel_hi:[1,0]
	v_exp_f32_e32 v118, v118
	v_exp_f32_e32 v119, v119
	global_store_dwordx4 v104, v[114:117], s[14:15] nt
	v_pk_mul_f32 v[146:147], v[82:83], v[192:193]
	v_mov_b32_dpp v110, v126 row_shl:1 row_mask:0xf bank_mask:0xf
	v_rcp_f32_e32 v107, v137
	v_pk_add_f32 v[118:119], v[118:119], 1.0 op_sel_hi:[1,0]
	v_rcp_f32_e32 v114, v118
	v_rcp_f32_e32 v115, v119
	v_pk_mul_f32 v[132:133], v[144:145], s[100:101] op_sel_hi:[1,0]
	v_exp_f32_e32 v132, v132
	v_exp_f32_e32 v133, v133
	v_pk_fma_f32 v[146:147], v[232:233], v[162:163], v[146:147]
	v_pk_mul_f32 v[114:115], v[130:131], v[114:115]
	v_pk_add_f32 v[132:133], v[132:133], 1.0 op_sel_hi:[1,0]
	v_pk_fma_f32 v[146:147], v[74:75], v[166:167], v[146:147]
	v_pk_mul_f32 v[116:117], v[114:115], v[178:179]
	v_rcp_f32_e32 v114, v132
	v_rcp_f32_e32 v115, v133
	v_pk_mul_f32 v[130:131], v[146:147], s[100:101] op_sel_hi:[1,0]
	v_exp_f32_e32 v130, v130
	v_exp_f32_e32 v131, v131
	v_pk_mul_f32 v[106:107], v[128:129], v[106:107]
	v_pk_mul_f32 v[118:119], v[112:113], v[20:21]
	v_pk_mul_f32 v[114:115], v[144:145], v[114:115]
	v_pk_fma_f32 v[118:119], v[134:135], v[18:19], v[118:119]
	v_pk_add_f32 v[130:131], v[130:131], 1.0 op_sel_hi:[1,0]
	v_pk_fma_f32 v[118:119], v[54:55], v[22:23], v[118:119]
	v_mov_b32_dpp v111, v127 row_shl:1 row_mask:0xf bank_mask:0xf
	v_pk_mul_f32 v[118:119], v[114:115], v[118:119]
	v_rcp_f32_e32 v114, v130
	v_rcp_f32_e32 v115, v131
	v_pk_mul_f32 v[128:129], v[124:125], v[12:13]
	v_pk_mul_f32 v[106:107], v[106:107], v[176:177]
	v_pk_fma_f32 v[126:127], v[126:127], v[10:11], v[128:129]
	v_pk_mul_f32 v[114:115], v[146:147], v[114:115]
	v_pk_fma_f32 v[126:127], v[52:53], v[14:15], v[126:127]
	v_add_u32_e32 v105, 0x2c00, v104
	v_pk_mul_f32 v[126:127], v[114:115], v[126:127]
	v_cvt_pk_f16_f32 v114, v106, v107
	v_pk_mul_f32 v[128:129], v[120:121], s[100:101] op_sel_hi:[1,0]
	v_exp_f32_e32 v128, v128
	v_exp_f32_e32 v129, v129
	v_cvt_pk_f16_f32 v115, v116, v117
	v_cvt_pk_f16_f32 v116, v118, v119
	v_cvt_pk_f16_f32 v117, v126, v127
	global_store_dwordx4 v105, v[114:117], s[14:15] nt
	v_pk_add_f32 v[128:129], v[128:129], 1.0 op_sel_hi:[1,0]
	v_rcp_f32_e32 v106, v128
	v_pk_mul_f32 v[116:117], v[122:123], s[100:101] op_sel_hi:[1,0]
	v_exp_f32_e32 v116, v116
	v_exp_f32_e32 v117, v117
	v_rcp_f32_e32 v107, v129
	v_pk_add_f32 v[116:117], v[116:117], 1.0 op_sel_hi:[1,0]
	v_rcp_f32_e32 v114, v116
	v_rcp_f32_e32 v115, v117
	v_pk_mul_f32 v[106:107], v[120:121], v[106:107]
	v_pk_mul_f32 v[116:117], v[80:81], s[100:101] op_sel_hi:[1,0]
	v_exp_f32_e32 v116, v116
	v_exp_f32_e32 v117, v117
	v_pk_mul_f32 v[100:101], v[106:107], v[100:101]
	v_pk_mul_f32 v[106:107], v[122:123], v[114:115]
	v_pk_add_f32 v[116:117], v[116:117], 1.0 op_sel_hi:[1,0]
	v_pk_mul_f32 v[102:103], v[106:107], v[102:103]
	v_rcp_f32_e32 v106, v116
	v_rcp_f32_e32 v107, v117
	v_pk_fma_f32 v[68:69], v[60:61], v[164:165], v[68:69]
	v_pk_fma_f32 v[60:61], v[60:61], v[160:161], v[168:169]
	v_pk_mul_f32 v[160:161], v[74:75], v[192:193]
	v_pk_mul_f32 v[70:71], v[208:209], v[70:71] op_sel_hi:[0,1]
	v_pk_fma_f32 v[82:83], v[82:83], v[162:163], v[160:161]
	v_pk_mul_f32 v[114:115], v[54:55], v[20:21]
	v_pk_fma_f32 v[82:83], v[70:71], v[166:167], v[82:83]
	v_pk_mul_f32 v[80:81], v[80:81], v[106:107]
	v_mul_f32_e32 v105, 0xbfb8aa3b, v82
	v_mul_f32_e32 v106, 0xbfb8aa3b, v83
	v_pk_fma_f32 v[112:113], v[112:113], v[18:19], v[114:115]
	v_exp_f32_e32 v105, v105
	v_exp_f32_e32 v114, v106
	v_pk_fma_f32 v[112:113], v[30:31], v[22:23], v[112:113]
	v_pk_mul_f32 v[160:161], v[70:71], v[192:193]
	v_pk_mul_f32 v[106:107], v[80:81], v[112:113]
	v_add_f32_e32 v80, 1.0, v105
	v_add_f32_e32 v81, 1.0, v114
	v_rcp_f32_e32 v80, v80
	v_rcp_f32_e32 v81, v81
	v_pk_mul_f32 v[112:113], v[52:53], v[12:13]
	v_add_u32_e32 v105, 0x5800, v104
	v_pk_fma_f32 v[112:113], v[124:125], v[10:11], v[112:113]
	v_pk_mul_f32 v[80:81], v[82:83], v[80:81]
	v_pk_fma_f32 v[112:113], v[28:29], v[14:15], v[112:113]
	v_cvt_pk_f16_f32 v82, v106, v107
	v_pk_mul_f32 v[112:113], v[80:81], v[112:113]
	v_cvt_pk_f16_f32 v80, v100, v101
	v_pk_mul_f32 v[100:101], v[48:49], s[100:101] op_sel_hi:[1,0]
	v_exp_f32_e32 v100, v100
	v_exp_f32_e32 v101, v101
	v_cvt_pk_f16_f32 v81, v102, v103
	v_cvt_pk_f16_f32 v83, v112, v113
	global_store_dwordx4 v105, v[80:83], s[14:15] nt
	v_pk_fma_f32 v[74:75], v[74:75], v[162:163], v[160:161]
	v_pk_mul_f32 v[160:161], v[66:67], v[192:193]
	v_pk_add_f32 v[80:81], v[100:101], 1.0 op_sel_hi:[1,0]
	v_rcp_f32_e32 v80, v80
	v_rcp_f32_e32 v81, v81
	v_pk_mul_f32 v[82:83], v[50:51], s[100:101] op_sel_hi:[1,0]
	v_exp_f32_e32 v82, v82
	v_pk_mul_f32 v[48:49], v[48:49], v[80:81]
	v_pk_mul_f32 v[80:81], v[72:73], s[100:101] op_sel_hi:[1,0]
	v_exp_f32_e32 v80, v80
	v_exp_f32_e32 v81, v81
	v_exp_f32_e32 v83, v83
	v_pk_add_f32 v[80:81], v[80:81], 1.0 op_sel_hi:[1,0]
	v_rcp_f32_e32 v80, v80
	v_rcp_f32_e32 v81, v81
	v_pk_add_f32 v[82:83], v[82:83], 1.0 op_sel_hi:[1,0]
	v_rcp_f32_e32 v82, v82
	v_rcp_f32_e32 v83, v83
	v_pk_fma_f32 v[74:75], v[66:67], v[166:167], v[74:75]
	v_pk_mul_f32 v[72:73], v[72:73], v[80:81]
	v_pk_mul_f32 v[80:81], v[74:75], s[100:101] op_sel_hi:[1,0]
	v_exp_f32_e32 v80, v80
	v_exp_f32_e32 v81, v81
	v_pk_mul_f32 v[50:51], v[50:51], v[82:83]
	v_pk_mul_f32 v[82:83], v[30:31], v[20:21]
	v_pk_mul_f32 v[48:49], v[48:49], v[96:97]
	v_pk_fma_f32 v[54:55], v[54:55], v[18:19], v[82:83]
; __device__ __forceinline__ float silu_f(float x) { return x * __builtin_amdgcn_rcpf(1.0f + __expf(-x)); }
;     __device__ __forceinline__ void operator()(Acc& acc, const Unit& u, int wr, int wc, int fr, int fq, LAS unsigned char* lds, int tid) const {
;     ...
;         for (int ai = 0; ai < 2; ++ai)
; #pragma unroll
;             for (int m = 0; m < 4; ++m) {
;                 f32x4 a[2];
; #pragma unroll
;                 for (int n = 0; n < 2; ++n)
; #pragma unroll
;                     for (int e = 0; e < 4; ++e) a[n][e] = silu_f(acc[ai][0][m][n][e]) * acc[ai][1][m][n][e];
;                 store_h8_nt((h16*)((char*)ACT + (((tok0 + tl0 + 4u * ai + m) * (unsigned)FF + colo) << 1)), a[0], a[1]);
;                 asm volatile("" ::: "memory");
	v_pk_mul_f32 v[50:51], v[50:51], v[98:99]
	v_pk_fma_f32 v[54:55], v[26:27], v[22:23], v[54:55]
	v_cvt_pk_f16_f32 v48, v48, v49
	v_pk_mul_f32 v[54:55], v[72:73], v[54:55]
	v_pk_add_f32 v[72:73], v[80:81], 1.0 op_sel_hi:[1,0]
	v_rcp_f32_e32 v72, v72
	v_rcp_f32_e32 v73, v73
	v_pk_mul_f32 v[80:81], v[28:29], v[12:13]
	v_cvt_pk_f16_f32 v49, v50, v51
	v_pk_fma_f32 v[52:53], v[52:53], v[10:11], v[80:81]
	v_pk_mul_f32 v[72:73], v[74:75], v[72:73]
	v_pk_fma_f32 v[52:53], v[24:25], v[14:15], v[52:53]
	v_cvt_pk_f16_f32 v50, v54, v55
	v_pk_mul_f32 v[52:53], v[72:73], v[52:53]
	v_add_u32_e32 v72, 0x8400, v104
	v_cvt_pk_f16_f32 v51, v52, v53
	v_pk_mul_f32 v[52:53], v[44:45], s[100:101] op_sel_hi:[1,0]
	v_exp_f32_e32 v52, v52
	v_exp_f32_e32 v53, v53
	global_store_dwordx4 v72, v[48:51], s[14:15] nt
	v_pk_fma_f32 v[70:71], v[70:71], v[162:163], v[160:161]
	v_pk_mul_f32 v[160:161], v[62:63], v[192:193]
	v_pk_add_f32 v[48:49], v[52:53], 1.0 op_sel_hi:[1,0]
	v_pk_mul_f32 v[50:51], v[46:47], s[100:101] op_sel_hi:[1,0]
	v_rcp_f32_e32 v48, v48
	v_exp_f32_e32 v50, v50
	v_exp_f32_e32 v51, v51
	v_rcp_f32_e32 v49, v49
	v_pk_fma_f32 v[70:71], v[62:63], v[166:167], v[70:71]
	v_pk_add_f32 v[50:51], v[50:51], 1.0 op_sel_hi:[1,0]
	v_pk_mul_f32 v[44:45], v[44:45], v[48:49]
	v_pk_mul_f32 v[48:49], v[68:69], s[100:101] op_sel_hi:[1,0]
	v_rcp_f32_e32 v50, v50
	v_rcp_f32_e32 v51, v51
	v_exp_f32_e32 v48, v48
	v_exp_f32_e32 v49, v49
	v_pk_mul_f32 v[44:45], v[44:45], v[92:93]
	v_pk_mul_f32 v[46:47], v[46:47], v[50:51]
	v_pk_add_f32 v[48:49], v[48:49], 1.0 op_sel_hi:[1,0]
	v_pk_mul_f32 v[50:51], v[26:27], v[20:21]
	v_rcp_f32_e32 v48, v48
	v_rcp_f32_e32 v49, v49
	v_pk_fma_f32 v[30:31], v[30:31], v[18:19], v[50:51]
	v_pk_mul_f32 v[50:51], v[70:71], s[100:101] op_sel_hi:[1,0]
	v_exp_f32_e32 v50, v50
	v_exp_f32_e32 v51, v51
	v_pk_fma_f32 v[30:31], v[16:17], v[22:23], v[30:31]
	v_pk_mul_f32 v[48:49], v[68:69], v[48:49]
	v_pk_mul_f32 v[46:47], v[46:47], v[94:95]
	v_pk_mul_f32 v[30:31], v[48:49], v[30:31]
	v_pk_add_f32 v[48:49], v[50:51], 1.0 op_sel_hi:[1,0]
	v_rcp_f32_e32 v48, v48
	v_rcp_f32_e32 v49, v49
	v_pk_mul_f32 v[50:51], v[24:25], v[12:13]
	v_cvt_pk_f16_f32 v30, v30, v31
	v_pk_fma_f32 v[28:29], v[28:29], v[10:11], v[50:51]
	v_pk_mul_f32 v[48:49], v[70:71], v[48:49]
	v_pk_fma_f32 v[28:29], v[8:9], v[14:15], v[28:29]
	v_add_u32_e32 v50, 0xb000, v104
	v_pk_mul_f32 v[48:49], v[48:49], v[28:29]
	v_cvt_pk_f16_f32 v28, v44, v45
	v_pk_mul_f32 v[44:45], v[40:41], s[100:101] op_sel_hi:[1,0]
	v_exp_f32_e32 v44, v44
	v_exp_f32_e32 v45, v45
	v_cvt_pk_f16_f32 v29, v46, v47
	v_cvt_pk_f16_f32 v31, v48, v49
	global_store_dwordx4 v50, v[28:31], s[14:15] nt
	v_pk_fma_f32 v[66:67], v[66:67], v[162:163], v[160:161]
	v_pk_fma_f32 v[90:91], v[78:79], v[194:195], v[90:91]
	v_pk_add_f32 v[28:29], v[44:45], 1.0 op_sel_hi:[1,0]
	v_pk_mul_f32 v[30:31], v[42:43], s[100:101] op_sel_hi:[1,0]
	v_rcp_f32_e32 v28, v28
	v_exp_f32_e32 v30, v30
	v_exp_f32_e32 v31, v31
	v_rcp_f32_e32 v29, v29
	v_pk_fma_f32 v[66:67], v[58:59], v[166:167], v[66:67]
	v_pk_add_f32 v[30:31], v[30:31], 1.0 op_sel_hi:[1,0]
	v_pk_mul_f32 v[28:29], v[40:41], v[28:29]
	v_pk_mul_f32 v[40:41], v[64:65], s[100:101] op_sel_hi:[1,0]
	v_rcp_f32_e32 v30, v30
	v_rcp_f32_e32 v31, v31
	v_exp_f32_e32 v40, v40
	v_exp_f32_e32 v41, v41
	v_pk_mul_f32 v[28:29], v[28:29], v[88:89]
	v_pk_mul_f32 v[30:31], v[42:43], v[30:31]
	v_pk_add_f32 v[40:41], v[40:41], 1.0 op_sel_hi:[1,0]
	v_pk_mul_f32 v[42:43], v[16:17], v[20:21]
	v_rcp_f32_e32 v40, v40
	v_rcp_f32_e32 v41, v41
	v_pk_fma_f32 v[26:27], v[26:27], v[18:19], v[42:43]
	v_pk_mul_f32 v[42:43], v[66:67], s[100:101] op_sel_hi:[1,0]
	v_exp_f32_e32 v42, v42
	v_exp_f32_e32 v43, v43
	v_pk_fma_f32 v[26:27], v[2:3], v[22:23], v[26:27]
	v_pk_mul_f32 v[40:41], v[64:65], v[40:41]
	v_pk_mul_f32 v[30:31], v[30:31], v[90:91]
	v_pk_mul_f32 v[26:27], v[40:41], v[26:27]
	v_pk_add_f32 v[40:41], v[42:43], 1.0 op_sel_hi:[1,0]
	v_rcp_f32_e32 v40, v40
	v_rcp_f32_e32 v41, v41
	v_pk_mul_f32 v[42:43], v[8:9], v[12:13]
	v_pk_fma_f32 v[60:61], v[234:235], v[164:165], v[60:61]
	v_pk_fma_f32 v[24:25], v[24:25], v[10:11], v[42:43]
	v_pk_mul_f32 v[40:41], v[66:67], v[40:41]
	v_pk_fma_f32 v[24:25], v[4:5], v[14:15], v[24:25]
	v_add_u32_e32 v42, 0xdc00, v104
	v_pk_mul_f32 v[40:41], v[40:41], v[24:25]
	v_cvt_pk_f16_f32 v24, v28, v29
; #define PG8_BAR __builtin_amdgcn_s_barrier()
; __device__ __forceinline__ float silu_f(float x) { return x * __builtin_amdgcn_rcpf(1.0f + __expf(-x)); }
; template <class Prob, class Epi, bool I8 = false, bool ALIGN_EPI = true, bool SP2 = true>
; __device__ __forceinline__ void gemm_phase(LAS unsigned char* lds, int wave, const Prob& P, const Epi& E) {
;     ...
;         if (!has_next) break;
;         if (!cur.keep) {
; #pragma unroll
;         for (int a = 0; a < 2; ++a)
; #pragma unroll
;             for (int b = 0; b < 2; ++b)
; #pragma unroll
;                 for (int m = 0; m < 4; ++m)
; #pragma unroll
;                     for (int n = 0; n < 2; ++n) acc[a][b][m][n] = (f32x4){0.f, 0.f, 0.f, 0.f};
;         }
;         cur = nxt; cA = nA; cB = nB; ++ui;
;         if constexpr (ALIGN_EPI) { if (wr == 1) PG8_BAR; }
;     __device__ __forceinline__ void operator()(Acc& acc, const Unit& u, int wr, int wc, int fr, int fq, LAS unsigned char* lds, int tid) const {
;     ...
;         for (int ai = 0; ai < 2; ++ai)
; #pragma unroll
;             for (int m = 0; m < 4; ++m) {
;                 f32x4 a[2];
; #pragma unroll
;                 for (int n = 0; n < 2; ++n)
; #pragma unroll
;                     for (int e = 0; e < 4; ++e) a[n][e] = silu_f(acc[ai][0][m][n][e]) * acc[ai][1][m][n][e];
;                 store_h8_nt((h16*)((char*)ACT + (((tok0 + tl0 + 4u * ai + m) * (unsigned)FF + colo) << 1)), a[0], a[1]);
;                 asm volatile("" ::: "memory");
	v_pk_mul_f32 v[28:29], v[36:37], s[100:101] op_sel_hi:[1,0]
	v_exp_f32_e32 v28, v28
	v_exp_f32_e32 v29, v29
	v_cvt_pk_f16_f32 v25, v30, v31
	v_cvt_pk_f16_f32 v26, v26, v27
	v_cvt_pk_f16_f32 v27, v40, v41
	global_store_dwordx4 v42, v[24:27], s[14:15] nt
	v_pk_mul_f32 v[160:161], v[58:59], v[192:193]
	v_pk_mul_f32 v[30:31], v[2:3], v[20:21]
	v_pk_add_f32 v[24:25], v[28:29], 1.0 op_sel_hi:[1,0]
	v_pk_mul_f32 v[28:29], v[60:61], s[100:101] op_sel_hi:[1,0]
	v_exp_f32_e32 v28, v28
	v_exp_f32_e32 v29, v29
	v_pk_fma_f32 v[62:63], v[62:63], v[162:163], v[160:161]
	v_pk_fma_f32 v[62:63], v[230:231], v[166:167], v[62:63]
	v_pk_add_f32 v[28:29], v[28:29], 1.0 op_sel_hi:[1,0]
	v_pk_mul_f32 v[26:27], v[38:39], s[100:101] op_sel_hi:[1,0]
	v_rcp_f32_e32 v28, v28
	v_rcp_f32_e32 v29, v29
	v_pk_fma_f32 v[16:17], v[16:17], v[18:19], v[30:31]
	v_pk_mul_f32 v[30:31], v[62:63], s[100:101] op_sel_hi:[1,0]
	v_exp_f32_e32 v26, v26
	v_exp_f32_e32 v27, v27
	v_exp_f32_e32 v30, v30
	v_exp_f32_e32 v31, v31
	v_pk_fma_f32 v[16:17], v[6:7], v[22:23], v[16:17]
	v_pk_mul_f32 v[28:29], v[60:61], v[28:29]
	v_pk_add_f32 v[26:27], v[26:27], 1.0 op_sel_hi:[1,0]
	v_pk_mul_f32 v[16:17], v[28:29], v[16:17]
	v_pk_add_f32 v[28:29], v[30:31], 1.0 op_sel_hi:[1,0]
	v_rcp_f32_e32 v24, v24
	v_rcp_f32_e32 v25, v25
	v_rcp_f32_e32 v26, v26
	v_rcp_f32_e32 v27, v27
	v_rcp_f32_e32 v28, v28
	v_rcp_f32_e32 v29, v29
	v_pk_mul_f32 v[30:31], v[4:5], v[12:13]
	v_pk_fma_f32 v[86:87], v[238:239], v[194:195], v[86:87]
	v_pk_fma_f32 v[8:9], v[8:9], v[10:11], v[30:31]
	v_pk_mul_f32 v[24:25], v[36:37], v[24:25]
	v_pk_mul_f32 v[26:27], v[38:39], v[26:27]
	v_pk_fma_f32 v[8:9], v[0:1], v[14:15], v[8:9]
	v_pk_mul_f32 v[28:29], v[62:63], v[28:29]
	v_pk_mul_f32 v[24:25], v[24:25], v[84:85]
	v_pk_mul_f32 v[26:27], v[26:27], v[86:87]
	v_pk_mul_f32 v[8:9], v[28:29], v[8:9]
	v_pk_fma_f32 v[56:57], v[164:165], v[172:173], v[56:57]
	v_add_u32_e32 v28, 0x10800, v104
	v_cvt_pk_f16_f32 v24, v24, v25
	v_cvt_pk_f16_f32 v25, v26, v27
	v_cvt_pk_f16_f32 v26, v16, v17
	v_cvt_pk_f16_f32 v27, v8, v9
	global_store_dwordx4 v28, v[24:27], s[14:15] nt
	v_pk_mul_f32 v[58:59], v[58:59], v[162:163]
	s_nop 0
	v_pk_mul_f32 v[24:25], v[56:57], s[100:101] op_sel_hi:[1,0]
	v_exp_f32_e32 v24, v24
	v_exp_f32_e32 v25, v25
	v_pk_fma_f32 v[58:59], v[230:231], v[192:193], v[58:59]
	v_pk_mul_f32 v[8:9], v[32:33], s[100:101] op_sel_hi:[1,0]
	v_pk_fma_f32 v[58:59], v[166:167], v[174:175], v[58:59]
	v_pk_add_f32 v[24:25], v[24:25], 1.0 op_sel_hi:[1,0]
	v_pk_mul_f32 v[16:17], v[34:35], s[100:101] op_sel_hi:[1,0]
	v_rcp_f32_e32 v24, v24
	v_rcp_f32_e32 v25, v25
	v_pk_mul_f32 v[2:3], v[2:3], v[18:19]
	v_pk_mul_f32 v[18:19], v[58:59], s[100:101] op_sel_hi:[1,0]
	v_exp_f32_e32 v8, v8
	v_exp_f32_e32 v9, v9
	v_exp_f32_e32 v16, v16
	v_exp_f32_e32 v17, v17
	v_exp_f32_e32 v18, v18
	v_exp_f32_e32 v19, v19
	v_mov_b32_dpp v108, v134 row_shl:1 row_mask:0xf bank_mask:0xf
	v_mov_b32_dpp v109, v135 row_shl:1 row_mask:0xf bank_mask:0xf
	v_pk_fma_f32 v[2:3], v[6:7], v[20:21], v[2:3]
	v_pk_mul_f32 v[6:7], v[56:57], v[24:25]
	v_pk_fma_f32 v[2:3], v[22:23], v[108:109], v[2:3]
	v_pk_add_f32 v[8:9], v[8:9], 1.0 op_sel_hi:[1,0]
	v_pk_add_f32 v[16:17], v[16:17], 1.0 op_sel_hi:[1,0]
	v_pk_mul_f32 v[2:3], v[6:7], v[2:3]
	v_pk_add_f32 v[6:7], v[18:19], 1.0 op_sel_hi:[1,0]
	v_rcp_f32_e32 v8, v8
	v_rcp_f32_e32 v9, v9
	v_rcp_f32_e32 v16, v16
	v_rcp_f32_e32 v17, v17
	v_rcp_f32_e32 v6, v6
	v_rcp_f32_e32 v7, v7
	v_pk_mul_f32 v[78:79], v[78:79], v[214:215]
	v_pk_mul_f32 v[4:5], v[4:5], v[10:11]
	v_pk_fma_f32 v[78:79], v[238:239], v[198:199], v[78:79]
	v_pk_fma_f32 v[0:1], v[0:1], v[12:13], v[4:5]
	v_pk_fma_f32 v[78:79], v[194:195], v[206:207], v[78:79]
	v_pk_mul_f32 v[8:9], v[32:33], v[8:9]
	v_pk_mul_f32 v[16:17], v[34:35], v[16:17]
	v_pk_fma_f32 v[0:1], v[14:15], v[110:111], v[0:1]
	v_pk_mul_f32 v[4:5], v[58:59], v[6:7]
	v_pk_mul_f32 v[8:9], v[8:9], v[76:77]
	v_pk_mul_f32 v[16:17], v[16:17], v[78:79]
	v_pk_mul_f32 v[4:5], v[4:5], v[0:1]
	v_add_u32_e32 v6, 0x13400, v104
	v_cvt_pk_f16_f32 v0, v8, v9
	v_cvt_pk_f16_f32 v1, v16, v17
	v_cvt_pk_f16_f32 v2, v2, v3
	v_cvt_pk_f16_f32 v3, v4, v5
	global_store_dwordx4 v6, v[0:3], s[14:15] nt
	s_cmp_eq_u32 s101, 0
	s_cbranch_scc1 .Lh1065_exit
	s_cmp_eq_u64 s[16:17], 0
	s_cbranch_scc1 .Lpeel_1065
	s_barrier
	s_branch .Lpeel_1065
